# GEMM K-loops: M0 write placed before the preceding MFMA (which supplies the wait state), s_nop per DMA piece removed
# baseline (speedup 1.0000x reference)
.Lg42_loop:
	s_and_b32 s17, s16, 0x8000
	s_xor_b32 s18, s17, 0x8000
	v_add_u32_e32 v132, v134, v84
	v_add_u32_e32 v133, v135, v84
	ds_read_b128 v[152:155], v132
	ds_read_b128 v[156:159], v132 offset:2048
	ds_read_b128 v[160:163], v132 offset:4096
	ds_read_b128 v[164:167], v132 offset:6144
	s_waitcnt lgkmcnt(4)
	v_mfma_f32_16x16x32_bf16 v[60:63], v[88:91], v[92:95], v[60:63]
	v_mfma_f32_16x16x32_bf16 v[56:59], v[88:91], v[100:103], v[56:59]
	v_mfma_f32_16x16x32_bf16 v[52:55], v[88:91], v[108:111], v[52:55]
	v_mfma_f32_16x16x32_bf16 v[48:51], v[88:91], v[116:119], v[48:51]
	ds_read_b128 v[168:171], v133 offset:16384
	ds_read_b128 v[172:175], v133 offset:18432
	ds_read_b128 v[176:179], v133 offset:20480
	ds_read_b128 v[180:183], v133 offset:22528
	v_mfma_f32_16x16x32_bf16 v[44:47], v[96:99], v[92:95], v[44:47]
	v_mfma_f32_16x16x32_bf16 v[40:43], v[96:99], v[100:103], v[40:43]
	v_mfma_f32_16x16x32_bf16 v[36:39], v[96:99], v[108:111], v[36:39]
	v_mfma_f32_16x16x32_bf16 v[32:35], v[96:99], v[116:119], v[32:35]
	v_mfma_f32_16x16x32_bf16 v[28:31], v[104:107], v[92:95], v[28:31]
	v_mfma_f32_16x16x32_bf16 v[24:27], v[104:107], v[100:103], v[24:27]
	v_mfma_f32_16x16x32_bf16 v[20:23], v[104:107], v[108:111], v[20:23]
	v_mfma_f32_16x16x32_bf16 v[16:19], v[104:107], v[116:119], v[16:19]
	v_mfma_f32_16x16x32_bf16 v[12:15], v[112:115], v[92:95], v[12:15]
	v_mfma_f32_16x16x32_bf16 v[8:11], v[112:115], v[100:103], v[8:11]
	v_mfma_f32_16x16x32_bf16 v[4:7], v[112:115], v[108:111], v[4:7]
	v_mfma_f32_16x16x32_bf16 v[0:3], v[112:115], v[116:119], v[0:3]
	s_waitcnt vmcnt(0) lgkmcnt(0)
	s_barrier
	v_add_u32_e32 v128, s17, v82
	s_add_i32 s17, s18, 32
	v_add_u32_e32 v134, s17, v85
	v_add_u32_e32 v135, s17, v83
	v_add_u32_e32 v132, v134, v86
	v_add_u32_e32 v133, v135, v86
	ds_read_b128 v[88:91], v132
	ds_read_b128 v[96:99], v132 offset:2048
	ds_read_b128 v[104:107], v132 offset:4096
	ds_read_b128 v[112:115], v132 offset:6144
	ds_read_b128 v[92:95], v133 offset:16384
	ds_read_b128 v[100:103], v133 offset:18432
	ds_read_b128 v[108:111], v133 offset:20480
	ds_read_b128 v[116:119], v133 offset:22528
	v_readfirstlane_b32 s18, v128
	s_mov_b32 m0, s18
	v_mfma_f32_16x16x32_bf16 v[60:63], v[152:155], v[168:171], v[60:63]
	global_load_lds_dwordx4 v64, s[98:99]
	v_mfma_f32_16x16x32_bf16 v[56:59], v[152:155], v[172:175], v[56:59]
	s_add_i32 m0, s18, 0x4000
	v_mfma_f32_16x16x32_bf16 v[52:55], v[152:155], v[176:179], v[52:55]
	global_load_lds_dwordx4 v72, s[100:101]
	v_mfma_f32_16x16x32_bf16 v[48:51], v[152:155], v[180:183], v[48:51]
	s_add_i32 m0, s18, 0x400
	v_mfma_f32_16x16x32_bf16 v[44:47], v[156:159], v[168:171], v[44:47]
	global_load_lds_dwordx4 v66, s[98:99]
	v_mfma_f32_16x16x32_bf16 v[40:43], v[156:159], v[172:175], v[40:43]
	s_add_i32 m0, s18, 0x4400
	v_mfma_f32_16x16x32_bf16 v[36:39], v[156:159], v[176:179], v[36:39]
	global_load_lds_dwordx4 v74, s[100:101]
	v_mfma_f32_16x16x32_bf16 v[32:35], v[156:159], v[180:183], v[32:35]
	s_add_i32 m0, s18, 0x800
	v_mfma_f32_16x16x32_bf16 v[28:31], v[160:163], v[168:171], v[28:31]
	global_load_lds_dwordx4 v68, s[98:99]
	v_mfma_f32_16x16x32_bf16 v[24:27], v[160:163], v[172:175], v[24:27]
	s_add_i32 m0, s18, 0x4800
	v_mfma_f32_16x16x32_bf16 v[20:23], v[160:163], v[176:179], v[20:23]
	global_load_lds_dwordx4 v76, s[100:101]
	v_mfma_f32_16x16x32_bf16 v[16:19], v[160:163], v[180:183], v[16:19]
	s_add_i32 m0, s18, 0xc00
	v_mfma_f32_16x16x32_bf16 v[12:15], v[164:167], v[168:171], v[12:15]
	global_load_lds_dwordx4 v70, s[98:99]
	v_mfma_f32_16x16x32_bf16 v[8:11], v[164:167], v[172:175], v[8:11]
	s_add_i32 m0, s18, 0x4c00
	v_mfma_f32_16x16x32_bf16 v[4:7], v[164:167], v[176:179], v[4:7]
	global_load_lds_dwordx4 v78, s[100:101]
	v_mfma_f32_16x16x32_bf16 v[0:3], v[164:167], v[180:183], v[0:3]
	s_add_i32 s16, s16, 0x8000
	s_add_u32 s42, s42, 0x80
	s_addc_u32 s43, s43, 0
	s_add_u32 s98, s98, 0x80
	s_addc_u32 s99, s99, 0
	s_add_u32 s100, s100, 0x80
	s_addc_u32 s101, s101, 0
	s_cmpk_lg_i32 s42, 0x1580
	s_cbranch_scc1 .Lg42_loop
	s_and_b32 s17, s16, 0x8000
	s_xor_b32 s18, s17, 0x8000
	v_add_u32_e32 v132, v134, v84
	v_add_u32_e32 v133, v135, v84
	ds_read_b128 v[152:155], v132
	ds_read_b128 v[156:159], v132 offset:2048
	ds_read_b128 v[160:163], v132 offset:4096
	ds_read_b128 v[164:167], v132 offset:6144
	s_waitcnt lgkmcnt(4)
	v_mfma_f32_16x16x32_bf16 v[60:63], v[88:91], v[92:95], v[60:63]
	v_mfma_f32_16x16x32_bf16 v[56:59], v[88:91], v[100:103], v[56:59]
	v_mfma_f32_16x16x32_bf16 v[52:55], v[88:91], v[108:111], v[52:55]
	v_mfma_f32_16x16x32_bf16 v[48:51], v[88:91], v[116:119], v[48:51]
	ds_read_b128 v[168:171], v133 offset:16384
	ds_read_b128 v[172:175], v133 offset:18432
	ds_read_b128 v[176:179], v133 offset:20480
	ds_read_b128 v[180:183], v133 offset:22528
	v_mfma_f32_16x16x32_bf16 v[44:47], v[96:99], v[92:95], v[44:47]
	v_mfma_f32_16x16x32_bf16 v[40:43], v[96:99], v[100:103], v[40:43]
	v_mfma_f32_16x16x32_bf16 v[36:39], v[96:99], v[108:111], v[36:39]
	v_mfma_f32_16x16x32_bf16 v[32:35], v[96:99], v[116:119], v[32:35]
	v_mfma_f32_16x16x32_bf16 v[28:31], v[104:107], v[92:95], v[28:31]
	v_mfma_f32_16x16x32_bf16 v[24:27], v[104:107], v[100:103], v[24:27]
	v_mfma_f32_16x16x32_bf16 v[20:23], v[104:107], v[108:111], v[20:23]
	v_mfma_f32_16x16x32_bf16 v[16:19], v[104:107], v[116:119], v[16:19]
	v_mfma_f32_16x16x32_bf16 v[12:15], v[112:115], v[92:95], v[12:15]
	v_mfma_f32_16x16x32_bf16 v[8:11], v[112:115], v[100:103], v[8:11]
	v_mfma_f32_16x16x32_bf16 v[4:7], v[112:115], v[108:111], v[4:7]
	v_mfma_f32_16x16x32_bf16 v[0:3], v[112:115], v[116:119], v[0:3]
	s_waitcnt vmcnt(0) lgkmcnt(0)
	s_barrier
	v_mfma_f32_16x16x32_bf16 v[60:63], v[152:155], v[168:171], v[60:63]
	v_mfma_f32_16x16x32_bf16 v[56:59], v[152:155], v[172:175], v[56:59]
	v_mfma_f32_16x16x32_bf16 v[52:55], v[152:155], v[176:179], v[52:55]
	v_mfma_f32_16x16x32_bf16 v[48:51], v[152:155], v[180:183], v[48:51]
	v_mfma_f32_16x16x32_bf16 v[44:47], v[156:159], v[168:171], v[44:47]
	v_mfma_f32_16x16x32_bf16 v[40:43], v[156:159], v[172:175], v[40:43]
	v_mfma_f32_16x16x32_bf16 v[36:39], v[156:159], v[176:179], v[36:39]
	v_mfma_f32_16x16x32_bf16 v[32:35], v[156:159], v[180:183], v[32:35]
	v_mfma_f32_16x16x32_bf16 v[28:31], v[160:163], v[168:171], v[28:31]
	v_mfma_f32_16x16x32_bf16 v[24:27], v[160:163], v[172:175], v[24:27]
	v_mfma_f32_16x16x32_bf16 v[20:23], v[160:163], v[176:179], v[20:23]
	v_mfma_f32_16x16x32_bf16 v[16:19], v[160:163], v[180:183], v[16:19]
	v_mfma_f32_16x16x32_bf16 v[12:15], v[164:167], v[168:171], v[12:15]
	v_mfma_f32_16x16x32_bf16 v[8:11], v[164:167], v[172:175], v[8:11]
	v_mfma_f32_16x16x32_bf16 v[4:7], v[164:167], v[176:179], v[4:7]
	v_mfma_f32_16x16x32_bf16 v[0:3], v[164:167], v[180:183], v[0:3]
	v_add_u32_e32 v82, 32, v85
	v_add_u32_e32 v83, 32, v83
	v_add_u32_e32 v85, v82, v86
	ds_read_b128 v[64:67], v85 offset:32768
	v_add_u32_e32 v98, v83, v86
	ds_read_b128 v[72:75], v85 offset:34816
	ds_read_b128 v[86:89], v85 offset:36864
	ds_read_b128 v[94:97], v85 offset:38912
	ds_read_b128 v[90:93], v98 offset:53248
	ds_read_b128 v[68:71], v98 offset:49152
	ds_read_b128 v[76:79], v98 offset:51200
	ds_read_b128 v[98:101], v98 offset:55296
	s_waitcnt lgkmcnt(3)
	v_mfma_f32_16x16x32_bf16 v[52:55], v[64:67], v[90:93], v[52:55]
	s_add_i32 s3, s3, s2
	s_cmpk_gt_u32 s3, 0x7f
	v_mfma_f32_16x16x32_bf16 v[36:39], v[72:75], v[90:93], v[36:39]
	v_mfma_f32_16x16x32_bf16 v[20:23], v[86:89], v[90:93], v[20:23]
	v_mfma_f32_16x16x32_bf16 v[4:7], v[94:97], v[90:93], v[4:7]
	v_add_u32_e32 v90, v82, v84
	s_waitcnt lgkmcnt(2)
	v_mfma_f32_16x16x32_bf16 v[60:63], v[64:67], v[68:71], v[60:63]
	s_waitcnt lgkmcnt(1)
	v_mfma_f32_16x16x32_bf16 v[56:59], v[64:67], v[76:79], v[56:59]
	s_waitcnt lgkmcnt(0)
	v_mfma_f32_16x16x32_bf16 v[48:51], v[64:67], v[98:101], v[48:51]
	v_mfma_f32_16x16x32_bf16 v[44:47], v[72:75], v[68:71], v[44:47]
	v_mfma_f32_16x16x32_bf16 v[40:43], v[72:75], v[76:79], v[40:43]
	v_mfma_f32_16x16x32_bf16 v[32:35], v[72:75], v[98:101], v[32:35]
	v_mfma_f32_16x16x32_bf16 v[28:31], v[86:89], v[68:71], v[28:31]
	v_mfma_f32_16x16x32_bf16 v[24:27], v[86:89], v[76:79], v[24:27]
	v_mfma_f32_16x16x32_bf16 v[16:19], v[86:89], v[98:101], v[16:19]
	v_mfma_f32_16x16x32_bf16 v[12:15], v[94:97], v[68:71], v[12:15]
	v_mfma_f32_16x16x32_bf16 v[8:11], v[94:97], v[76:79], v[8:11]
	v_mfma_f32_16x16x32_bf16 v[0:3], v[94:97], v[98:101], v[0:3]
	ds_read_b128 v[64:67], v90 offset:32768
	v_add_u32_e32 v94, v83, v84
	ds_read_b128 v[72:75], v90 offset:34816
	ds_read_b128 v[82:85], v90 offset:36864
	ds_read_b128 v[90:93], v90 offset:38912
	ds_read_b128 v[68:71], v94 offset:49152
	ds_read_b128 v[76:79], v94 offset:51200
	ds_read_b128 v[86:89], v94 offset:53248
	ds_read_b128 v[94:97], v94 offset:55296
	s_waitcnt lgkmcnt(3)
	v_mfma_f32_16x16x32_bf16 v[60:63], v[64:67], v[68:71], v[60:63]
	s_waitcnt vmcnt(0)
	s_waitcnt lgkmcnt(0)
	s_barrier
	v_mfma_f32_16x16x32_bf16 v[56:59], v[64:67], v[76:79], v[56:59]
	s_nop 4
	v_cvt_pk_bf16_f32 v60, v60, v61
	v_cvt_pk_bf16_f32 v61, v62, v63
	v_mfma_f32_16x16x32_bf16 v[52:55], v[64:67], v[86:89], v[52:55]
	v_mfma_f32_16x16x32_bf16 v[48:51], v[64:67], v[94:97], v[48:51]
	v_and_b32_e32 v65, 0x4f, v80
	v_or_b32_e32 v66, s10, v65
	v_add_u32_e32 v64, s8, v81
	v_mfma_f32_16x16x32_bf16 v[12:15], v[90:93], v[68:71], v[12:15]
	v_ashrrev_i32_e32 v67, 31, v66
	v_ashrrev_i32_e32 v65, 31, v64
	v_lshlrev_b64 v[64:65], 1, v[64:65]
	v_mfma_f32_16x16x32_bf16 v[44:47], v[72:75], v[68:71], v[44:47]
	v_mfma_f32_16x16x32_bf16 v[28:31], v[82:85], v[68:71], v[28:31]
	v_lshlrev_b64 v[68:69], 11, v[66:67]
	v_lshl_add_u64 v[68:69], s[72:73], 0, v[68:69]
	v_lshrrev_b32_e32 v67, 1, v80
	v_lshl_add_u64 v[68:69], v[68:69], 0, v[64:65]
	v_and_b32_e32 v192, 24, v67
	v_lshl_add_u64 v[68:69], v[68:69], 0, v[192:193]
	v_cvt_pk_bf16_f32 v12, v12, v13
	v_cvt_pk_bf16_f32 v13, v14, v15
	global_store_dwordx2 v[68:69], v[12:13], off offset:96
	v_or_b32_e32 v12, 16, v66
	v_mfma_f32_16x16x32_bf16 v[8:11], v[90:93], v[76:79], v[8:11]
	v_ashrrev_i32_e32 v13, 31, v12
	v_lshlrev_b64 v[12:13], 11, v[12:13]
	v_lshl_add_u64 v[12:13], s[72:73], 0, v[12:13]
	v_lshl_add_u64 v[12:13], v[12:13], 0, v[64:65]
	v_lshl_add_u64 v[12:13], v[12:13], 0, v[192:193]
	s_nop 2
	v_cvt_pk_bf16_f32 v8, v8, v9
	v_cvt_pk_bf16_f32 v9, v10, v11
	global_store_dwordx2 v[12:13], v[8:9], off offset:96
	v_or_b32_e32 v8, 32, v66
	v_mfma_f32_16x16x32_bf16 v[4:7], v[90:93], v[86:89], v[4:7]
	v_ashrrev_i32_e32 v9, 31, v8
	v_lshlrev_b64 v[8:9], 11, v[8:9]
	v_lshl_add_u64 v[8:9], s[72:73], 0, v[8:9]
	v_lshl_add_u64 v[8:9], v[8:9], 0, v[64:65]
	v_lshl_add_u64 v[8:9], v[8:9], 0, v[192:193]
	s_nop 2
	v_cvt_pk_bf16_f32 v4, v4, v5
	v_cvt_pk_bf16_f32 v5, v6, v7
	global_store_dwordx2 v[8:9], v[4:5], off offset:96
	v_or_b32_e32 v4, 48, v66
	v_ashrrev_i32_e32 v5, 31, v4
	v_mfma_f32_16x16x32_bf16 v[40:43], v[72:75], v[76:79], v[40:43]
	v_lshlrev_b64 v[4:5], 11, v[4:5]
	v_lshl_add_u64 v[4:5], s[72:73], 0, v[4:5]
	v_lshl_add_u64 v[4:5], v[4:5], 0, v[64:65]
	v_mfma_f32_16x16x32_bf16 v[36:39], v[72:75], v[86:89], v[36:39]
	v_cvt_pk_bf16_f32 v14, v56, v57
	v_cvt_pk_bf16_f32 v15, v58, v59
	v_cvt_pk_bf16_f32 v10, v52, v53
	v_mfma_f32_16x16x32_bf16 v[32:35], v[72:75], v[94:97], v[32:35]
	v_cvt_pk_bf16_f32 v11, v54, v55
	v_lshl_add_u64 v[4:5], v[4:5], 0, v[192:193]
	v_cvt_pk_bf16_f32 v6, v48, v49
	v_mfma_f32_16x16x32_bf16 v[24:27], v[82:85], v[76:79], v[24:27]
	v_cvt_pk_bf16_f32 v7, v50, v51
	global_store_dwordx2 v[12:13], v[14:15], off
	v_cvt_pk_bf16_f32 v14, v40, v41
	v_mfma_f32_16x16x32_bf16 v[20:23], v[82:85], v[86:89], v[20:23]
	v_cvt_pk_bf16_f32 v15, v42, v43
	global_store_dwordx2 v[8:9], v[10:11], off
	v_cvt_pk_bf16_f32 v10, v36, v37
	v_mfma_f32_16x16x32_bf16 v[16:19], v[82:85], v[94:97], v[16:19]
	v_cvt_pk_bf16_f32 v11, v38, v39
	global_store_dwordx2 v[4:5], v[6:7], off
	v_cvt_pk_bf16_f32 v6, v32, v33
	v_mfma_f32_16x16x32_bf16 v[0:3], v[90:93], v[94:97], v[0:3]
	v_cvt_pk_bf16_f32 v7, v34, v35
	v_cvt_pk_bf16_f32 v44, v44, v45
	v_cvt_pk_bf16_f32 v45, v46, v47
	v_cvt_pk_bf16_f32 v28, v28, v29
	v_cvt_pk_bf16_f32 v29, v30, v31
	global_store_dwordx2 v[12:13], v[14:15], off offset:32
	v_cvt_pk_bf16_f32 v14, v24, v25
	v_cvt_pk_bf16_f32 v15, v26, v27
	global_store_dwordx2 v[8:9], v[10:11], off offset:32
	v_cvt_pk_bf16_f32 v10, v20, v21
	v_cvt_pk_bf16_f32 v11, v22, v23
	global_store_dwordx2 v[4:5], v[6:7], off offset:32
	v_cvt_pk_bf16_f32 v6, v16, v17
	v_cvt_pk_bf16_f32 v7, v18, v19
	v_cvt_pk_bf16_f32 v0, v0, v1
	v_cvt_pk_bf16_f32 v1, v2, v3
	global_store_dwordx2 v[68:69], v[60:61], off
	global_store_dwordx2 v[68:69], v[44:45], off offset:32
	global_store_dwordx2 v[68:69], v[28:29], off offset:64
	global_store_dwordx2 v[12:13], v[14:15], off offset:64
	global_store_dwordx2 v[8:9], v[10:11], off offset:64
	global_store_dwordx2 v[4:5], v[6:7], off offset:64
	global_store_dwordx2 v[4:5], v[0:1], off offset:96
	s_cbranch_scc0 .LBB0_41

.Lg65_loop:
	s_and_b32 s17, s16, 0x8000
	s_xor_b32 s18, s17, 0x8000
	v_add_u32_e32 v132, v134, v83
	v_add_u32_e32 v133, v135, v83
	ds_read_b128 v[152:155], v132
	ds_read_b128 v[156:159], v132 offset:2048
	ds_read_b128 v[160:163], v132 offset:4096
	ds_read_b128 v[164:167], v132 offset:6144
	s_waitcnt lgkmcnt(4)
	v_mfma_f32_16x16x32_bf16 v[60:63], v[88:91], v[92:95], v[60:63]
	v_mfma_f32_16x16x32_bf16 v[56:59], v[88:91], v[100:103], v[56:59]
	v_mfma_f32_16x16x32_bf16 v[52:55], v[88:91], v[108:111], v[52:55]
	v_mfma_f32_16x16x32_bf16 v[48:51], v[88:91], v[116:119], v[48:51]
	ds_read_b128 v[168:171], v133 offset:16384
	ds_read_b128 v[172:175], v133 offset:18432
	ds_read_b128 v[176:179], v133 offset:20480
	ds_read_b128 v[180:183], v133 offset:22528
	v_mfma_f32_16x16x32_bf16 v[44:47], v[96:99], v[92:95], v[44:47]
	v_mfma_f32_16x16x32_bf16 v[40:43], v[96:99], v[100:103], v[40:43]
	v_mfma_f32_16x16x32_bf16 v[36:39], v[96:99], v[108:111], v[36:39]
	v_mfma_f32_16x16x32_bf16 v[32:35], v[96:99], v[116:119], v[32:35]
	v_mfma_f32_16x16x32_bf16 v[28:31], v[104:107], v[92:95], v[28:31]
	v_mfma_f32_16x16x32_bf16 v[24:27], v[104:107], v[100:103], v[24:27]
	v_mfma_f32_16x16x32_bf16 v[20:23], v[104:107], v[108:111], v[20:23]
	v_mfma_f32_16x16x32_bf16 v[16:19], v[104:107], v[116:119], v[16:19]
	v_mfma_f32_16x16x32_bf16 v[12:15], v[112:115], v[92:95], v[12:15]
	v_mfma_f32_16x16x32_bf16 v[8:11], v[112:115], v[100:103], v[8:11]
	v_mfma_f32_16x16x32_bf16 v[4:7], v[112:115], v[108:111], v[4:7]
	v_mfma_f32_16x16x32_bf16 v[0:3], v[112:115], v[116:119], v[0:3]
	s_waitcnt vmcnt(0) lgkmcnt(0)
	s_barrier
	v_add_u32_e32 v128, s17, v82
	s_add_i32 s17, s18, 32
	v_add_u32_e32 v134, s17, v85
	v_add_u32_e32 v135, s17, v86
	v_add_u32_e32 v132, v134, v84
	v_add_u32_e32 v133, v135, v84
	ds_read_b128 v[88:91], v132
	ds_read_b128 v[96:99], v132 offset:2048
	ds_read_b128 v[104:107], v132 offset:4096
	ds_read_b128 v[112:115], v132 offset:6144
	ds_read_b128 v[92:95], v133 offset:16384
	ds_read_b128 v[100:103], v133 offset:18432
	ds_read_b128 v[108:111], v133 offset:20480
	ds_read_b128 v[116:119], v133 offset:22528
	v_readfirstlane_b32 s18, v128
	s_mov_b32 m0, s18
	v_mfma_f32_16x16x32_bf16 v[60:63], v[152:155], v[168:171], v[60:63]
	global_load_lds_dwordx4 v64, s[98:99]
	v_mfma_f32_16x16x32_bf16 v[56:59], v[152:155], v[172:175], v[56:59]
	s_add_i32 m0, s18, 0x4000
	v_mfma_f32_16x16x32_bf16 v[52:55], v[152:155], v[176:179], v[52:55]
	global_load_lds_dwordx4 v72, s[100:101]
	v_mfma_f32_16x16x32_bf16 v[48:51], v[152:155], v[180:183], v[48:51]
	s_add_i32 m0, s18, 0x400
	v_mfma_f32_16x16x32_bf16 v[44:47], v[156:159], v[168:171], v[44:47]
	global_load_lds_dwordx4 v66, s[98:99]
	v_mfma_f32_16x16x32_bf16 v[40:43], v[156:159], v[172:175], v[40:43]
	s_add_i32 m0, s18, 0x4400
	v_mfma_f32_16x16x32_bf16 v[36:39], v[156:159], v[176:179], v[36:39]
	global_load_lds_dwordx4 v74, s[100:101]
	v_mfma_f32_16x16x32_bf16 v[32:35], v[156:159], v[180:183], v[32:35]
	s_add_i32 m0, s18, 0x800
	v_mfma_f32_16x16x32_bf16 v[28:31], v[160:163], v[168:171], v[28:31]
	global_load_lds_dwordx4 v68, s[98:99]
	v_mfma_f32_16x16x32_bf16 v[24:27], v[160:163], v[172:175], v[24:27]
	s_add_i32 m0, s18, 0x4800
	v_mfma_f32_16x16x32_bf16 v[20:23], v[160:163], v[176:179], v[20:23]
	global_load_lds_dwordx4 v76, s[100:101]
	v_mfma_f32_16x16x32_bf16 v[16:19], v[160:163], v[180:183], v[16:19]
	s_add_i32 m0, s18, 0xc00
	v_mfma_f32_16x16x32_bf16 v[12:15], v[164:167], v[168:171], v[12:15]
	global_load_lds_dwordx4 v70, s[98:99]
	v_mfma_f32_16x16x32_bf16 v[8:11], v[164:167], v[172:175], v[8:11]
	s_add_i32 m0, s18, 0x4c00
	v_mfma_f32_16x16x32_bf16 v[4:7], v[164:167], v[176:179], v[4:7]
	global_load_lds_dwordx4 v78, s[100:101]
	v_mfma_f32_16x16x32_bf16 v[0:3], v[164:167], v[180:183], v[0:3]
	s_add_i32 s16, s16, 0x8000
	s_add_u32 s42, s42, 0x80
	s_addc_u32 s43, s43, 0
	s_add_u32 s98, s98, 0x80
	s_addc_u32 s99, s99, 0
	s_add_u32 s100, s100, 0x80
	s_addc_u32 s101, s101, 0
	s_cmpk_lg_i32 s42, 0x780
	s_cbranch_scc1 .Lg65_loop
	s_and_b32 s17, s16, 0x8000
	s_xor_b32 s18, s17, 0x8000
	v_add_u32_e32 v132, v134, v83
	v_add_u32_e32 v133, v135, v83
	ds_read_b128 v[152:155], v132
	ds_read_b128 v[156:159], v132 offset:2048
	ds_read_b128 v[160:163], v132 offset:4096
	ds_read_b128 v[164:167], v132 offset:6144
	s_waitcnt lgkmcnt(4)
	v_mfma_f32_16x16x32_bf16 v[60:63], v[88:91], v[92:95], v[60:63]
	v_mfma_f32_16x16x32_bf16 v[56:59], v[88:91], v[100:103], v[56:59]
	v_mfma_f32_16x16x32_bf16 v[52:55], v[88:91], v[108:111], v[52:55]
	v_mfma_f32_16x16x32_bf16 v[48:51], v[88:91], v[116:119], v[48:51]
	ds_read_b128 v[168:171], v133 offset:16384
	ds_read_b128 v[172:175], v133 offset:18432
	ds_read_b128 v[176:179], v133 offset:20480
	ds_read_b128 v[180:183], v133 offset:22528
	v_mfma_f32_16x16x32_bf16 v[44:47], v[96:99], v[92:95], v[44:47]
	v_mfma_f32_16x16x32_bf16 v[40:43], v[96:99], v[100:103], v[40:43]
	v_mfma_f32_16x16x32_bf16 v[36:39], v[96:99], v[108:111], v[36:39]
	v_mfma_f32_16x16x32_bf16 v[32:35], v[96:99], v[116:119], v[32:35]
	v_mfma_f32_16x16x32_bf16 v[28:31], v[104:107], v[92:95], v[28:31]
	v_mfma_f32_16x16x32_bf16 v[24:27], v[104:107], v[100:103], v[24:27]
	v_mfma_f32_16x16x32_bf16 v[20:23], v[104:107], v[108:111], v[20:23]
	v_mfma_f32_16x16x32_bf16 v[16:19], v[104:107], v[116:119], v[16:19]
	v_mfma_f32_16x16x32_bf16 v[12:15], v[112:115], v[92:95], v[12:15]
	v_mfma_f32_16x16x32_bf16 v[8:11], v[112:115], v[100:103], v[8:11]
	v_mfma_f32_16x16x32_bf16 v[4:7], v[112:115], v[108:111], v[4:7]
	v_mfma_f32_16x16x32_bf16 v[0:3], v[112:115], v[116:119], v[0:3]
	s_waitcnt vmcnt(0) lgkmcnt(0)
	s_barrier
	v_mfma_f32_16x16x32_bf16 v[60:63], v[152:155], v[168:171], v[60:63]
	v_mfma_f32_16x16x32_bf16 v[56:59], v[152:155], v[172:175], v[56:59]
	v_mfma_f32_16x16x32_bf16 v[52:55], v[152:155], v[176:179], v[52:55]
	v_mfma_f32_16x16x32_bf16 v[48:51], v[152:155], v[180:183], v[48:51]
	v_mfma_f32_16x16x32_bf16 v[44:47], v[156:159], v[168:171], v[44:47]
	v_mfma_f32_16x16x32_bf16 v[40:43], v[156:159], v[172:175], v[40:43]
	v_mfma_f32_16x16x32_bf16 v[36:39], v[156:159], v[176:179], v[36:39]
	v_mfma_f32_16x16x32_bf16 v[32:35], v[156:159], v[180:183], v[32:35]
	v_mfma_f32_16x16x32_bf16 v[28:31], v[160:163], v[168:171], v[28:31]
	v_mfma_f32_16x16x32_bf16 v[24:27], v[160:163], v[172:175], v[24:27]
	v_mfma_f32_16x16x32_bf16 v[20:23], v[160:163], v[176:179], v[20:23]
	v_mfma_f32_16x16x32_bf16 v[16:19], v[160:163], v[180:183], v[16:19]
	v_mfma_f32_16x16x32_bf16 v[12:15], v[164:167], v[168:171], v[12:15]
	v_mfma_f32_16x16x32_bf16 v[8:11], v[164:167], v[172:175], v[8:11]
	v_mfma_f32_16x16x32_bf16 v[4:7], v[164:167], v[176:179], v[4:7]
	v_mfma_f32_16x16x32_bf16 v[0:3], v[164:167], v[180:183], v[0:3]
	v_add_u32_e32 v100, 32, v85
	v_add_u32_e32 v96, v100, v84
	ds_read_b128 v[64:67], v96 offset:32768
	ds_read_b128 v[72:75], v96 offset:38912
	ds_read_b128 v[88:91], v96 offset:36864
	ds_read_b128 v[96:99], v96 offset:34816
	v_add_u32_e32 v82, 32, v86
	v_add_u32_e32 v92, v82, v84
	ds_read_b128 v[68:71], v92 offset:55296
	ds_read_b128 v[76:79], v92 offset:49152
	ds_read_b128 v[84:87], v92 offset:53248
	ds_read_b128 v[92:95], v92 offset:51200
	s_waitcnt lgkmcnt(0)
	v_mfma_f32_16x16x32_bf16 v[56:59], v[64:67], v[92:95], v[56:59]
	v_readlane_b32 s44, v252, 11
	v_readlane_b32 s45, v252, 12
	s_add_i32 s11, s11, s5
	v_mfma_f32_16x16x32_bf16 v[44:47], v[96:99], v[76:79], v[44:47]
	s_cmp_ge_u32 s11, s3
	v_readlane_b32 s46, v252, 13
	v_readlane_b32 s47, v252, 14
	v_mfma_f32_16x16x32_bf16 v[40:43], v[96:99], v[92:95], v[40:43]
	v_readlane_b32 s48, v252, 15
	v_readlane_b32 s49, v252, 16
	v_readlane_b32 s50, v252, 17
	v_mfma_f32_16x16x32_bf16 v[36:39], v[96:99], v[84:87], v[36:39]
	v_readlane_b32 s51, v252, 18
	v_mfma_f32_16x16x32_bf16 v[32:35], v[96:99], v[68:71], v[32:35]
	v_mfma_f32_16x16x32_bf16 v[96:99], v[88:91], v[92:95], v[24:27]
	v_mfma_f32_16x16x32_bf16 v[92:95], v[72:75], v[92:95], v[8:11]
	s_nop 2
	v_add_u32_e32 v8, v100, v83
	v_mfma_f32_16x16x32_bf16 v[60:63], v[64:67], v[76:79], v[60:63]
	v_add_u32_e32 v9, v82, v83
	v_mfma_f32_16x16x32_bf16 v[52:55], v[64:67], v[84:87], v[52:55]
	v_mfma_f32_16x16x32_bf16 v[48:51], v[64:67], v[68:71], v[48:51]
	v_mfma_f32_16x16x32_bf16 v[64:67], v[88:91], v[76:79], v[28:31]
	v_mfma_f32_16x16x32_bf16 v[20:23], v[88:91], v[84:87], v[20:23]
	v_mfma_f32_16x16x32_bf16 v[88:91], v[88:91], v[68:71], v[16:19]
	v_mfma_f32_16x16x32_bf16 v[76:79], v[72:75], v[76:79], v[12:15]
	v_mfma_f32_16x16x32_bf16 v[4:7], v[72:75], v[84:87], v[4:7]
	v_mfma_f32_16x16x32_bf16 v[68:71], v[72:75], v[68:71], v[0:3]
	ds_read_b128 v[72:75], v9 offset:49152
	ds_read_b128 v[12:15], v8 offset:34816
	ds_read_b128 v[100:103], v8 offset:36864
	ds_read_b128 v[0:3], v8 offset:32768
	ds_read_b128 v[108:111], v8 offset:38912
	ds_read_b128 v[104:107], v9 offset:53248
	ds_read_b128 v[112:115], v9 offset:55296
	ds_read_b128 v[82:85], v9 offset:51200
	s_waitcnt lgkmcnt(4)
	v_mfma_f32_16x16x32_bf16 v[60:63], v[0:3], v[72:75], v[60:63]
	s_waitcnt vmcnt(0)
	s_waitcnt lgkmcnt(0)
	s_barrier
	v_mfma_f32_16x16x32_bf16 v[24:27], v[0:3], v[104:107], v[52:55]
	v_mfma_f32_16x16x32_bf16 v[44:47], v[12:15], v[72:75], v[44:47]
	v_mfma_f32_16x16x32_bf16 v[28:31], v[12:15], v[104:107], v[36:39]
	v_mfma_f32_16x16x32_bf16 v[36:39], v[100:103], v[72:75], v[64:67]
	v_mfma_f32_16x16x32_bf16 v[16:19], v[100:103], v[104:107], v[20:23]
	v_mfma_f32_16x16x32_bf16 v[52:55], v[108:111], v[72:75], v[76:79]
	v_mul_f32_e32 v72, 0xbfb8aa3b, v61
	v_exp_f32_e32 v72, v72
	v_mul_f32_e32 v73, 0xbfb8aa3b, v63
	v_mfma_f32_16x16x32_bf16 v[20:23], v[108:111], v[104:107], v[4:7]
	v_exp_f32_e32 v73, v73
	s_nop 0
	v_add_f32_e32 v73, 1.0, v73
	v_mfma_f32_16x16x32_bf16 v[4:7], v[108:111], v[112:115], v[68:71]
	v_rcp_f32_e32 v73, v73
	s_nop 1
	v_mul_f32_e32 v71, 0xbfb8aa3b, v60
	v_exp_f32_e32 v71, v71
	v_lshrrev_b32_e32 v70, 1, v80
	v_and_b32_e32 v192, 24, v70
	v_mfma_f32_16x16x32_bf16 v[56:59], v[0:3], v[82:85], v[56:59]
	v_add_f32_e32 v70, 1.0, v71
	v_add_f32_e32 v71, 1.0, v72
	v_mul_f32_e32 v72, 0xbfb8aa3b, v62
	v_exp_f32_e32 v72, v72
	v_rcp_f32_e32 v70, v70
	v_rcp_f32_e32 v71, v71
	v_mfma_f32_16x16x32_bf16 v[40:43], v[12:15], v[82:85], v[40:43]
	v_add_f32_e32 v72, 1.0, v72
	v_rcp_f32_e32 v72, v72
	v_pk_mul_f32 v[60:61], v[60:61], v[70:71]
	v_mfma_f32_16x16x32_bf16 v[12:15], v[12:15], v[112:115], v[32:35]
	v_mul_f32_e64 v44, v44, v60
	v_mul_f32_e64 v45, v45, v61
	v_pk_mul_f32 v[60:61], v[62:63], v[72:73]
	v_cvt_pk_bf16_f32 v44, v44, v45
	v_mul_f32_e32 v45, 0xbfb8aa3b, v36
	v_pk_mul_f32 v[46:47], v[46:47], v[60:61]
	v_exp_f32_e32 v60, v45
	v_mul_f32_e32 v45, 0xbfb8aa3b, v37
	v_exp_f32_e32 v61, v45
	v_cvt_pk_bf16_f32 v45, v46, v47
	v_add_f32_e32 v46, 1.0, v60
	v_mul_f32_e32 v60, 0xbfb8aa3b, v38
	v_add_f32_e32 v47, 1.0, v61
	v_mul_f32_e32 v61, 0xbfb8aa3b, v39
	v_exp_f32_e32 v60, v60
	v_exp_f32_e32 v61, v61
	v_rcp_f32_e32 v46, v46
	v_rcp_f32_e32 v47, v47
	v_add_f32_e32 v60, 1.0, v60
	v_add_f32_e32 v61, 1.0, v61
	v_rcp_f32_e32 v60, v60
	v_rcp_f32_e32 v61, v61
	v_add_u32_e32 v32, s8, v81
	v_and_b32_e32 v33, 0x4f, v80
	v_ashrrev_i32_e32 v32, 1, v32
	v_or_b32_e32 v74, s12, v33
	v_ashrrev_i32_e32 v33, 31, v32
	v_mov_b64_e32 v[34:35], s[44:45]
	s_movk_i32 s8, 0x1600
	v_pk_mul_f32 v[36:37], v[36:37], v[46:47]
	v_pk_mul_f32 v[38:39], v[38:39], v[60:61]
	v_mad_i64_i32 v[68:69], s[16:17], v74, s8, v[34:35]
	v_lshlrev_b64 v[32:33], 1, v[32:33]
	v_pk_mul_f32 v[36:37], v[52:53], v[36:37]
	v_pk_mul_f32 v[38:39], v[54:55], v[38:39]
	v_lshl_add_u64 v[68:69], v[68:69], 0, v[32:33]
	v_cvt_pk_bf16_f32 v36, v36, v37
	v_cvt_pk_bf16_f32 v37, v38, v39
	v_mul_f32_e32 v38, 0xbfb8aa3b, v56
	v_mul_f32_e32 v39, 0xbfb8aa3b, v57
	v_lshl_add_u64 v[68:69], v[68:69], 0, v[192:193]
	v_exp_f32_e32 v38, v38
	v_exp_f32_e32 v39, v39
	global_store_dwordx2 v[68:69], v[44:45], off
	v_mul_f32_e32 v44, 0xbfb8aa3b, v58
	v_mul_f32_e32 v45, 0xbfb8aa3b, v59
	v_exp_f32_e32 v44, v44
	v_exp_f32_e32 v45, v45
	v_add_f32_e32 v38, 1.0, v38
	v_add_f32_e32 v39, 1.0, v39
	v_rcp_f32_e32 v38, v38
	v_rcp_f32_e32 v39, v39
	v_add_f32_e32 v44, 1.0, v44
	v_add_f32_e32 v45, 1.0, v45
	v_mfma_f32_16x16x32_bf16 v[8:11], v[0:3], v[112:115], v[48:51]
	v_rcp_f32_e32 v44, v44
	v_rcp_f32_e32 v45, v45
	v_pk_mul_f32 v[38:39], v[56:57], v[38:39]
	v_mfma_f32_16x16x32_bf16 v[48:51], v[100:103], v[82:85], v[96:99]
	v_mul_f32_e64 v38, v40, v38
	v_mul_f32_e64 v39, v41, v39
	v_pk_mul_f32 v[40:41], v[58:59], v[44:45]
	v_cvt_pk_bf16_f32 v38, v38, v39
	v_pk_mul_f32 v[40:41], v[42:43], v[40:41]
	global_store_dwordx2 v[68:69], v[36:37], off offset:32
	s_nop 1
	v_mul_f32_e32 v39, 0xbfb8aa3b, v48
	v_exp_f32_e32 v42, v39
	v_mul_f32_e32 v39, 0xbfb8aa3b, v49
	v_exp_f32_e32 v43, v39
	v_cvt_pk_bf16_f32 v39, v40, v41
	v_add_f32_e32 v40, 1.0, v42
	v_mul_f32_e32 v42, 0xbfb8aa3b, v50
	v_add_f32_e32 v41, 1.0, v43
	v_mul_f32_e32 v43, 0xbfb8aa3b, v51
	v_exp_f32_e32 v42, v42
	v_exp_f32_e32 v43, v43
	v_or_b32_e32 v36, 16, v74
	v_rcp_f32_e32 v40, v40
	v_add_f32_e32 v42, 1.0, v42
	v_add_f32_e32 v43, 1.0, v43
	v_rcp_f32_e32 v41, v41
	v_rcp_f32_e32 v42, v42
	v_rcp_f32_e32 v43, v43
	v_mfma_f32_16x16x32_bf16 v[64:67], v[108:111], v[82:85], v[92:95]
	v_mad_i64_i32 v[36:37], s[16:17], v36, s8, v[34:35]
	v_lshl_add_u64 v[36:37], v[36:37], 0, v[32:33]
	v_lshl_add_u64 v[36:37], v[36:37], 0, v[192:193]
	global_store_dwordx2 v[36:37], v[38:39], off
	v_pk_mul_f32 v[38:39], v[48:49], v[40:41]
	v_pk_mul_f32 v[40:41], v[50:51], v[42:43]
	s_nop 1
	v_pk_mul_f32 v[38:39], v[64:65], v[38:39]
	v_pk_mul_f32 v[40:41], v[66:67], v[40:41]
	v_cvt_pk_bf16_f32 v38, v38, v39
	v_cvt_pk_bf16_f32 v39, v40, v41
	global_store_dwordx2 v[36:37], v[38:39], off offset:32
	v_mul_f32_e32 v38, 0xbfb8aa3b, v24
	v_mul_f32_e32 v39, 0xbfb8aa3b, v25
	v_exp_f32_e32 v38, v38
	v_exp_f32_e32 v39, v39
	v_mul_f32_e32 v40, 0xbfb8aa3b, v26
	v_mul_f32_e32 v41, 0xbfb8aa3b, v27
	v_add_f32_e32 v38, 1.0, v38
	v_add_f32_e32 v39, 1.0, v39
	v_rcp_f32_e32 v38, v38
	v_rcp_f32_e32 v39, v39
	v_exp_f32_e32 v40, v40
	v_exp_f32_e32 v41, v41
	v_mfma_f32_16x16x32_bf16 v[0:3], v[100:103], v[112:115], v[88:91]
	v_mul_f32_e64 v24, v24, v38
	v_mul_f32_e64 v25, v25, v39
	v_add_f32_e32 v40, 1.0, v40
	v_add_f32_e32 v41, 1.0, v41
	v_pk_mul_f32 v[24:25], v[28:29], v[24:25]
	v_rcp_f32_e32 v40, v40
	v_rcp_f32_e32 v41, v41
	v_cvt_pk_bf16_f32 v24, v24, v25
	v_mul_f32_e32 v25, 0xbfb8aa3b, v16
	v_exp_f32_e32 v28, v25
	v_mul_f32_e32 v25, 0xbfb8aa3b, v17
	v_exp_f32_e32 v29, v25
	v_pk_mul_f32 v[26:27], v[26:27], v[40:41]
	v_or_b32_e32 v36, 32, v74
	v_pk_mul_f32 v[26:27], v[30:31], v[26:27]
	v_mad_i64_i32 v[36:37], s[16:17], v36, s8, v[34:35]
	v_cvt_pk_bf16_f32 v25, v26, v27
	v_add_f32_e32 v26, 1.0, v28
	v_add_f32_e32 v27, 1.0, v29
	v_mul_f32_e32 v28, 0xbfb8aa3b, v18
	v_mul_f32_e32 v29, 0xbfb8aa3b, v19
	v_exp_f32_e32 v28, v28
	v_exp_f32_e32 v29, v29
	v_rcp_f32_e32 v26, v26
	v_rcp_f32_e32 v27, v27
	v_add_f32_e32 v28, 1.0, v28
	v_add_f32_e32 v29, 1.0, v29
	v_rcp_f32_e32 v28, v28
	v_rcp_f32_e32 v29, v29
	v_pk_mul_f32 v[16:17], v[16:17], v[26:27]
	v_lshl_add_u64 v[36:37], v[36:37], 0, v[32:33]
	v_pk_mul_f32 v[16:17], v[20:21], v[16:17]
	v_pk_mul_f32 v[18:19], v[18:19], v[28:29]
	v_cvt_pk_bf16_f32 v16, v16, v17
	v_pk_mul_f32 v[18:19], v[22:23], v[18:19]
	v_mul_f32_e32 v20, 0xbfb8aa3b, v10
	v_cvt_pk_bf16_f32 v17, v18, v19
	v_mul_f32_e32 v18, 0xbfb8aa3b, v8
	v_mul_f32_e32 v19, 0xbfb8aa3b, v9
	v_exp_f32_e32 v18, v18
	v_exp_f32_e32 v19, v19
	v_mul_f32_e32 v21, 0xbfb8aa3b, v11
	v_exp_f32_e32 v20, v20
	v_add_f32_e32 v18, 1.0, v18
	v_add_f32_e32 v19, 1.0, v19
	v_rcp_f32_e32 v18, v18
	v_rcp_f32_e32 v19, v19
	v_exp_f32_e32 v21, v21
	v_add_f32_e32 v20, 1.0, v20
	v_rcp_f32_e32 v20, v20
	v_pk_mul_f32 v[8:9], v[8:9], v[18:19]
	v_add_f32_e32 v21, 1.0, v21
	v_pk_mul_f32 v[8:9], v[12:13], v[8:9]
	v_rcp_f32_e32 v21, v21
	v_cvt_pk_bf16_f32 v8, v8, v9
	v_mul_f32_e32 v9, 0xbfb8aa3b, v0
	v_exp_f32_e32 v12, v9
	v_mul_f32_e32 v9, 0xbfb8aa3b, v1
	v_exp_f32_e32 v13, v9
	v_pk_mul_f32 v[10:11], v[10:11], v[20:21]
	v_lshl_add_u64 v[36:37], v[36:37], 0, v[192:193]
	v_pk_mul_f32 v[10:11], v[14:15], v[10:11]
	global_store_dwordx2 v[36:37], v[16:17], off offset:32
	v_cvt_pk_bf16_f32 v9, v10, v11
	v_add_f32_e32 v10, 1.0, v12
	v_add_f32_e32 v11, 1.0, v13
	v_mul_f32_e32 v12, 0xbfb8aa3b, v2
	v_mul_f32_e32 v13, 0xbfb8aa3b, v3
	v_exp_f32_e32 v12, v12
	v_exp_f32_e32 v13, v13
	v_rcp_f32_e32 v10, v10
	v_rcp_f32_e32 v11, v11
	v_add_f32_e32 v12, 1.0, v12
	v_add_f32_e32 v13, 1.0, v13
	v_rcp_f32_e32 v12, v12
	v_rcp_f32_e32 v13, v13
	v_or_b32_e32 v16, 48, v74
	v_mad_i64_i32 v[16:17], s[16:17], v16, s8, v[34:35]
	v_pk_mul_f32 v[0:1], v[0:1], v[10:11]
	v_pk_mul_f32 v[2:3], v[2:3], v[12:13]
	v_lshl_add_u64 v[16:17], v[16:17], 0, v[32:33]
	v_pk_mul_f32 v[0:1], v[4:5], v[0:1]
	v_pk_mul_f32 v[2:3], v[6:7], v[2:3]
	v_lshl_add_u64 v[16:17], v[16:17], 0, v[192:193]
	v_cvt_pk_bf16_f32 v0, v0, v1
	v_cvt_pk_bf16_f32 v1, v2, v3
	global_store_dwordx2 v[36:37], v[24:25], off
	global_store_dwordx2 v[16:17], v[8:9], off
	global_store_dwordx2 v[16:17], v[0:1], off offset:32
	s_cbranch_scc0 .LBB0_62

.Lg80_loop:
	s_and_b32 s12, s11, 0x8000
	s_xor_b32 s16, s12, 0x8000
	v_add_u32_e32 v132, v134, v84
	v_add_u32_e32 v133, v135, v84
	ds_read_b128 v[152:155], v132
	ds_read_b128 v[156:159], v132 offset:2048
	ds_read_b128 v[160:163], v132 offset:4096
	ds_read_b128 v[164:167], v132 offset:6144
	s_waitcnt lgkmcnt(4)
	v_mfma_f32_16x16x32_bf16 v[60:63], v[88:91], v[92:95], v[60:63]
	v_mfma_f32_16x16x32_bf16 v[56:59], v[88:91], v[100:103], v[56:59]
	v_mfma_f32_16x16x32_bf16 v[52:55], v[88:91], v[108:111], v[52:55]
	v_mfma_f32_16x16x32_bf16 v[48:51], v[88:91], v[116:119], v[48:51]
	ds_read_b128 v[168:171], v133 offset:16384
	ds_read_b128 v[172:175], v133 offset:18432
	ds_read_b128 v[176:179], v133 offset:20480
	ds_read_b128 v[180:183], v133 offset:22528
	v_mfma_f32_16x16x32_bf16 v[44:47], v[96:99], v[92:95], v[44:47]
	v_mfma_f32_16x16x32_bf16 v[40:43], v[96:99], v[100:103], v[40:43]
	v_mfma_f32_16x16x32_bf16 v[36:39], v[96:99], v[108:111], v[36:39]
	v_mfma_f32_16x16x32_bf16 v[32:35], v[96:99], v[116:119], v[32:35]
	v_mfma_f32_16x16x32_bf16 v[28:31], v[104:107], v[92:95], v[28:31]
	v_mfma_f32_16x16x32_bf16 v[24:27], v[104:107], v[100:103], v[24:27]
	v_mfma_f32_16x16x32_bf16 v[20:23], v[104:107], v[108:111], v[20:23]
	v_mfma_f32_16x16x32_bf16 v[16:19], v[104:107], v[116:119], v[16:19]
	v_mfma_f32_16x16x32_bf16 v[12:15], v[112:115], v[92:95], v[12:15]
	v_mfma_f32_16x16x32_bf16 v[8:11], v[112:115], v[100:103], v[8:11]
	v_mfma_f32_16x16x32_bf16 v[4:7], v[112:115], v[108:111], v[4:7]
	v_mfma_f32_16x16x32_bf16 v[0:3], v[112:115], v[116:119], v[0:3]
	s_waitcnt vmcnt(0) lgkmcnt(0)
	s_barrier
	v_add_u32_e32 v128, s12, v82
	s_add_i32 s12, s16, 32
	v_add_u32_e32 v134, s12, v85
	v_add_u32_e32 v135, s12, v83
	v_add_u32_e32 v132, v134, v86
	v_add_u32_e32 v133, v135, v86
	ds_read_b128 v[88:91], v132
	ds_read_b128 v[96:99], v132 offset:2048
	ds_read_b128 v[104:107], v132 offset:4096
	ds_read_b128 v[112:115], v132 offset:6144
	ds_read_b128 v[92:95], v133 offset:16384
	ds_read_b128 v[100:103], v133 offset:18432
	ds_read_b128 v[108:111], v133 offset:20480
	ds_read_b128 v[116:119], v133 offset:22528
	v_readfirstlane_b32 s16, v128
	s_mov_b32 m0, s16
	v_mfma_f32_16x16x32_bf16 v[60:63], v[152:155], v[168:171], v[60:63]
	global_load_lds_dwordx4 v64, s[98:99]
	v_mfma_f32_16x16x32_bf16 v[56:59], v[152:155], v[172:175], v[56:59]
	s_add_i32 m0, s16, 0x4000
	v_mfma_f32_16x16x32_bf16 v[52:55], v[152:155], v[176:179], v[52:55]
	global_load_lds_dwordx4 v72, s[100:101]
	v_mfma_f32_16x16x32_bf16 v[48:51], v[152:155], v[180:183], v[48:51]
	s_add_i32 m0, s16, 0x400
	v_mfma_f32_16x16x32_bf16 v[44:47], v[156:159], v[168:171], v[44:47]
	global_load_lds_dwordx4 v66, s[98:99]
	v_mfma_f32_16x16x32_bf16 v[40:43], v[156:159], v[172:175], v[40:43]
	s_add_i32 m0, s16, 0x4400
	v_mfma_f32_16x16x32_bf16 v[36:39], v[156:159], v[176:179], v[36:39]
	global_load_lds_dwordx4 v74, s[100:101]
	v_mfma_f32_16x16x32_bf16 v[32:35], v[156:159], v[180:183], v[32:35]
	s_add_i32 m0, s16, 0x800
	v_mfma_f32_16x16x32_bf16 v[28:31], v[160:163], v[168:171], v[28:31]
	global_load_lds_dwordx4 v68, s[98:99]
	v_mfma_f32_16x16x32_bf16 v[24:27], v[160:163], v[172:175], v[24:27]
	s_add_i32 m0, s16, 0x4800
	v_mfma_f32_16x16x32_bf16 v[20:23], v[160:163], v[176:179], v[20:23]
	global_load_lds_dwordx4 v76, s[100:101]
	v_mfma_f32_16x16x32_bf16 v[16:19], v[160:163], v[180:183], v[16:19]
	s_add_i32 m0, s16, 0xc00
	v_mfma_f32_16x16x32_bf16 v[12:15], v[164:167], v[168:171], v[12:15]
	global_load_lds_dwordx4 v70, s[98:99]
	v_mfma_f32_16x16x32_bf16 v[8:11], v[164:167], v[172:175], v[8:11]
	s_add_i32 m0, s16, 0x4c00
	v_mfma_f32_16x16x32_bf16 v[4:7], v[164:167], v[176:179], v[4:7]
	global_load_lds_dwordx4 v78, s[100:101]
	v_mfma_f32_16x16x32_bf16 v[0:3], v[164:167], v[180:183], v[0:3]
	s_add_i32 s11, s11, 0x8000
	s_add_u32 s40, s40, 0x80
	s_addc_u32 s41, s41, 0
	s_add_u32 s98, s98, 0x80
	s_addc_u32 s99, s99, 0
	s_add_u32 s100, s100, 0x80
	s_addc_u32 s101, s101, 0
	s_cmpk_lg_i32 s40, 0x780
	s_cbranch_scc1 .Lg80_loop
	s_and_b32 s12, s11, 0x8000
	s_xor_b32 s16, s12, 0x8000
	v_add_u32_e32 v132, v134, v84
	v_add_u32_e32 v133, v135, v84
	ds_read_b128 v[152:155], v132
	ds_read_b128 v[156:159], v132 offset:2048
	ds_read_b128 v[160:163], v132 offset:4096
	ds_read_b128 v[164:167], v132 offset:6144
	s_waitcnt lgkmcnt(4)
	v_mfma_f32_16x16x32_bf16 v[60:63], v[88:91], v[92:95], v[60:63]
	v_mfma_f32_16x16x32_bf16 v[56:59], v[88:91], v[100:103], v[56:59]
	v_mfma_f32_16x16x32_bf16 v[52:55], v[88:91], v[108:111], v[52:55]
	v_mfma_f32_16x16x32_bf16 v[48:51], v[88:91], v[116:119], v[48:51]
	ds_read_b128 v[168:171], v133 offset:16384
	ds_read_b128 v[172:175], v133 offset:18432
	ds_read_b128 v[176:179], v133 offset:20480
	ds_read_b128 v[180:183], v133 offset:22528
	v_mfma_f32_16x16x32_bf16 v[44:47], v[96:99], v[92:95], v[44:47]
	v_mfma_f32_16x16x32_bf16 v[40:43], v[96:99], v[100:103], v[40:43]
	v_mfma_f32_16x16x32_bf16 v[36:39], v[96:99], v[108:111], v[36:39]
	v_mfma_f32_16x16x32_bf16 v[32:35], v[96:99], v[116:119], v[32:35]
	v_mfma_f32_16x16x32_bf16 v[28:31], v[104:107], v[92:95], v[28:31]
	v_mfma_f32_16x16x32_bf16 v[24:27], v[104:107], v[100:103], v[24:27]
	v_mfma_f32_16x16x32_bf16 v[20:23], v[104:107], v[108:111], v[20:23]
	v_mfma_f32_16x16x32_bf16 v[16:19], v[104:107], v[116:119], v[16:19]
	v_mfma_f32_16x16x32_bf16 v[12:15], v[112:115], v[92:95], v[12:15]
	v_mfma_f32_16x16x32_bf16 v[8:11], v[112:115], v[100:103], v[8:11]
	v_mfma_f32_16x16x32_bf16 v[4:7], v[112:115], v[108:111], v[4:7]
	v_mfma_f32_16x16x32_bf16 v[0:3], v[112:115], v[116:119], v[0:3]
	s_waitcnt vmcnt(0) lgkmcnt(0)
	s_barrier
	v_mfma_f32_16x16x32_bf16 v[60:63], v[152:155], v[168:171], v[60:63]
	v_mfma_f32_16x16x32_bf16 v[56:59], v[152:155], v[172:175], v[56:59]
	v_mfma_f32_16x16x32_bf16 v[52:55], v[152:155], v[176:179], v[52:55]
	v_mfma_f32_16x16x32_bf16 v[48:51], v[152:155], v[180:183], v[48:51]
	v_mfma_f32_16x16x32_bf16 v[44:47], v[156:159], v[168:171], v[44:47]
	v_mfma_f32_16x16x32_bf16 v[40:43], v[156:159], v[172:175], v[40:43]
	v_mfma_f32_16x16x32_bf16 v[36:39], v[156:159], v[176:179], v[36:39]
	v_mfma_f32_16x16x32_bf16 v[32:35], v[156:159], v[180:183], v[32:35]
	v_mfma_f32_16x16x32_bf16 v[28:31], v[160:163], v[168:171], v[28:31]
	v_mfma_f32_16x16x32_bf16 v[24:27], v[160:163], v[172:175], v[24:27]
	v_mfma_f32_16x16x32_bf16 v[20:23], v[160:163], v[176:179], v[20:23]
	v_mfma_f32_16x16x32_bf16 v[16:19], v[160:163], v[180:183], v[16:19]
	v_mfma_f32_16x16x32_bf16 v[12:15], v[164:167], v[168:171], v[12:15]
	v_mfma_f32_16x16x32_bf16 v[8:11], v[164:167], v[172:175], v[8:11]
	v_mfma_f32_16x16x32_bf16 v[4:7], v[164:167], v[176:179], v[4:7]
	v_mfma_f32_16x16x32_bf16 v[0:3], v[164:167], v[180:183], v[0:3]
	v_add_u32_e32 v82, 32, v85
	v_add_u32_e32 v83, 32, v83
	v_add_u32_e32 v85, v82, v86
	ds_read_b128 v[64:67], v85 offset:32768
	v_add_u32_e32 v98, v83, v86
	ds_read_b128 v[72:75], v85 offset:34816
	ds_read_b128 v[86:89], v85 offset:36864
	ds_read_b128 v[94:97], v85 offset:38912
	ds_read_b128 v[90:93], v98 offset:53248
	ds_read_b128 v[68:71], v98 offset:49152
	ds_read_b128 v[76:79], v98 offset:51200
	ds_read_b128 v[98:101], v98 offset:55296
	s_waitcnt lgkmcnt(3)
	v_mfma_f32_16x16x32_bf16 v[52:55], v[64:67], v[90:93], v[52:55]
	s_add_i32 s2, s2, s8
	s_cmpk_gt_u32 s2, 0x7f
	v_mfma_f32_16x16x32_bf16 v[36:39], v[72:75], v[90:93], v[36:39]
	v_mfma_f32_16x16x32_bf16 v[20:23], v[86:89], v[90:93], v[20:23]
	v_mfma_f32_16x16x32_bf16 v[4:7], v[94:97], v[90:93], v[4:7]
	v_add_u32_e32 v90, v82, v84
	s_waitcnt lgkmcnt(2)
	v_mfma_f32_16x16x32_bf16 v[60:63], v[64:67], v[68:71], v[60:63]
	s_waitcnt lgkmcnt(1)
	v_mfma_f32_16x16x32_bf16 v[56:59], v[64:67], v[76:79], v[56:59]
	s_waitcnt lgkmcnt(0)
	v_mfma_f32_16x16x32_bf16 v[48:51], v[64:67], v[98:101], v[48:51]
	v_mfma_f32_16x16x32_bf16 v[44:47], v[72:75], v[68:71], v[44:47]
	v_mfma_f32_16x16x32_bf16 v[40:43], v[72:75], v[76:79], v[40:43]
	v_mfma_f32_16x16x32_bf16 v[32:35], v[72:75], v[98:101], v[32:35]
	v_mfma_f32_16x16x32_bf16 v[28:31], v[86:89], v[68:71], v[28:31]
	v_mfma_f32_16x16x32_bf16 v[24:27], v[86:89], v[76:79], v[24:27]
	v_mfma_f32_16x16x32_bf16 v[16:19], v[86:89], v[98:101], v[16:19]
	v_mfma_f32_16x16x32_bf16 v[12:15], v[94:97], v[68:71], v[12:15]
	v_mfma_f32_16x16x32_bf16 v[8:11], v[94:97], v[76:79], v[8:11]
	v_mfma_f32_16x16x32_bf16 v[0:3], v[94:97], v[98:101], v[0:3]
	ds_read_b128 v[64:67], v90 offset:32768
	v_add_u32_e32 v94, v83, v84
	ds_read_b128 v[72:75], v90 offset:34816
	ds_read_b128 v[82:85], v90 offset:36864
	ds_read_b128 v[90:93], v90 offset:38912
	ds_read_b128 v[68:71], v94 offset:49152
	ds_read_b128 v[76:79], v94 offset:51200
	ds_read_b128 v[86:89], v94 offset:53248
	ds_read_b128 v[94:97], v94 offset:55296
	s_waitcnt lgkmcnt(3)
	v_mfma_f32_16x16x32_bf16 v[60:63], v[64:67], v[68:71], v[60:63]
	s_waitcnt vmcnt(0)
	s_waitcnt lgkmcnt(0)
	s_barrier
	v_mfma_f32_16x16x32_bf16 v[56:59], v[64:67], v[76:79], v[56:59]
	s_nop 4
	v_cvt_pk_bf16_f32 v60, v60, v61
	v_cvt_pk_bf16_f32 v61, v62, v63
	v_mfma_f32_16x16x32_bf16 v[52:55], v[64:67], v[86:89], v[52:55]
	v_mfma_f32_16x16x32_bf16 v[48:51], v[64:67], v[94:97], v[48:51]
	v_and_b32_e32 v65, 0x4f, v80
	v_or_b32_e32 v66, s10, v65
	v_add_u32_e32 v64, s3, v81
	v_mfma_f32_16x16x32_bf16 v[12:15], v[90:93], v[68:71], v[12:15]
	v_ashrrev_i32_e32 v67, 31, v66
	v_ashrrev_i32_e32 v65, 31, v64
	v_lshlrev_b64 v[64:65], 1, v[64:65]
	v_mfma_f32_16x16x32_bf16 v[44:47], v[72:75], v[68:71], v[44:47]
	v_mfma_f32_16x16x32_bf16 v[28:31], v[82:85], v[68:71], v[28:31]
	v_lshlrev_b64 v[68:69], 11, v[66:67]
	v_lshl_add_u64 v[68:69], s[72:73], 0, v[68:69]
	v_lshrrev_b32_e32 v67, 1, v80
	v_lshl_add_u64 v[68:69], v[68:69], 0, v[64:65]
	v_and_b32_e32 v192, 24, v67
	v_lshl_add_u64 v[68:69], v[68:69], 0, v[192:193]
	v_cvt_pk_bf16_f32 v12, v12, v13
	v_cvt_pk_bf16_f32 v13, v14, v15
	global_store_dwordx2 v[68:69], v[12:13], off offset:96
	v_or_b32_e32 v12, 16, v66
	v_mfma_f32_16x16x32_bf16 v[8:11], v[90:93], v[76:79], v[8:11]
	v_ashrrev_i32_e32 v13, 31, v12
	v_lshlrev_b64 v[12:13], 11, v[12:13]
	v_lshl_add_u64 v[12:13], s[72:73], 0, v[12:13]
	v_lshl_add_u64 v[12:13], v[12:13], 0, v[64:65]
	v_lshl_add_u64 v[12:13], v[12:13], 0, v[192:193]
	s_nop 2
	v_cvt_pk_bf16_f32 v8, v8, v9
	v_cvt_pk_bf16_f32 v9, v10, v11
	global_store_dwordx2 v[12:13], v[8:9], off offset:96
	v_or_b32_e32 v8, 32, v66
	v_mfma_f32_16x16x32_bf16 v[4:7], v[90:93], v[86:89], v[4:7]
	v_ashrrev_i32_e32 v9, 31, v8
	v_lshlrev_b64 v[8:9], 11, v[8:9]
	v_lshl_add_u64 v[8:9], s[72:73], 0, v[8:9]
	v_lshl_add_u64 v[8:9], v[8:9], 0, v[64:65]
	v_lshl_add_u64 v[8:9], v[8:9], 0, v[192:193]
	s_nop 2
	v_cvt_pk_bf16_f32 v4, v4, v5
	v_cvt_pk_bf16_f32 v5, v6, v7
	global_store_dwordx2 v[8:9], v[4:5], off offset:96
	v_or_b32_e32 v4, 48, v66
	v_ashrrev_i32_e32 v5, 31, v4
	v_mfma_f32_16x16x32_bf16 v[40:43], v[72:75], v[76:79], v[40:43]
	v_lshlrev_b64 v[4:5], 11, v[4:5]
	v_lshl_add_u64 v[4:5], s[72:73], 0, v[4:5]
	v_lshl_add_u64 v[4:5], v[4:5], 0, v[64:65]
	v_mfma_f32_16x16x32_bf16 v[36:39], v[72:75], v[86:89], v[36:39]
	v_cvt_pk_bf16_f32 v14, v56, v57
	v_cvt_pk_bf16_f32 v15, v58, v59
	v_cvt_pk_bf16_f32 v10, v52, v53
	v_mfma_f32_16x16x32_bf16 v[32:35], v[72:75], v[94:97], v[32:35]
	v_cvt_pk_bf16_f32 v11, v54, v55
	v_lshl_add_u64 v[4:5], v[4:5], 0, v[192:193]
	v_cvt_pk_bf16_f32 v6, v48, v49
	v_mfma_f32_16x16x32_bf16 v[24:27], v[82:85], v[76:79], v[24:27]
	v_cvt_pk_bf16_f32 v7, v50, v51
	global_store_dwordx2 v[12:13], v[14:15], off
	v_cvt_pk_bf16_f32 v14, v40, v41
	v_mfma_f32_16x16x32_bf16 v[20:23], v[82:85], v[86:89], v[20:23]
	v_cvt_pk_bf16_f32 v15, v42, v43
	global_store_dwordx2 v[8:9], v[10:11], off
	v_cvt_pk_bf16_f32 v10, v36, v37
	v_mfma_f32_16x16x32_bf16 v[16:19], v[82:85], v[94:97], v[16:19]
	v_cvt_pk_bf16_f32 v11, v38, v39
	global_store_dwordx2 v[4:5], v[6:7], off
	v_cvt_pk_bf16_f32 v6, v32, v33
	v_mfma_f32_16x16x32_bf16 v[0:3], v[90:93], v[94:97], v[0:3]
	v_cvt_pk_bf16_f32 v7, v34, v35
	v_cvt_pk_bf16_f32 v44, v44, v45
	v_cvt_pk_bf16_f32 v45, v46, v47
	v_cvt_pk_bf16_f32 v28, v28, v29
	v_cvt_pk_bf16_f32 v29, v30, v31
	global_store_dwordx2 v[12:13], v[14:15], off offset:32
	v_cvt_pk_bf16_f32 v14, v24, v25
	v_cvt_pk_bf16_f32 v15, v26, v27
	global_store_dwordx2 v[8:9], v[10:11], off offset:32
	v_cvt_pk_bf16_f32 v10, v20, v21
	v_cvt_pk_bf16_f32 v11, v22, v23
	global_store_dwordx2 v[4:5], v[6:7], off offset:32
	v_cvt_pk_bf16_f32 v6, v16, v17
	v_cvt_pk_bf16_f32 v7, v18, v19
	v_cvt_pk_bf16_f32 v0, v0, v1
	v_cvt_pk_bf16_f32 v1, v2, v3
	global_store_dwordx2 v[68:69], v[60:61], off
	global_store_dwordx2 v[68:69], v[44:45], off offset:32
	global_store_dwordx2 v[68:69], v[28:29], off offset:64
	global_store_dwordx2 v[12:13], v[14:15], off offset:64
	global_store_dwordx2 v[8:9], v[10:11], off offset:64
	global_store_dwordx2 v[4:5], v[6:7], off offset:64
	global_store_dwordx2 v[4:5], v[0:1], off offset:96
	s_cbranch_scc0 .LBB0_79

.Lg255_loop:
	s_and_b32 s10, s8, 0x8000
	s_xor_b32 s12, s10, 0x8000
	v_add_u32_e32 v132, v134, v86
	v_add_u32_e32 v133, v135, v86
	ds_read_b128 v[152:155], v132
	ds_read_b128 v[156:159], v132 offset:2048
	ds_read_b128 v[160:163], v132 offset:4096
	ds_read_b128 v[164:167], v132 offset:6144
	s_waitcnt lgkmcnt(4)
	v_mfma_f32_16x16x32_bf16 v[52:55], v[90:93], v[94:97], v[52:55]
	v_mfma_f32_16x16x32_bf16 v[48:51], v[90:93], v[102:105], v[48:51]
	v_mfma_f32_16x16x32_bf16 v[44:47], v[90:93], v[110:113], v[44:47]
	v_mfma_f32_16x16x32_bf16 v[40:43], v[90:93], v[118:121], v[40:43]
	ds_read_b128 v[168:171], v133 offset:16384
	ds_read_b128 v[172:175], v133 offset:18432
	ds_read_b128 v[176:179], v133 offset:20480
	ds_read_b128 v[180:183], v133 offset:22528
	v_mfma_f32_16x16x32_bf16 v[36:39], v[98:101], v[94:97], v[36:39]
	v_mfma_f32_16x16x32_bf16 v[32:35], v[98:101], v[102:105], v[32:35]
	v_mfma_f32_16x16x32_bf16 v[28:31], v[98:101], v[110:113], v[28:31]
	v_mfma_f32_16x16x32_bf16 v[24:27], v[98:101], v[118:121], v[24:27]
	v_mfma_f32_16x16x32_bf16 v[20:23], v[106:109], v[94:97], v[20:23]
	v_mfma_f32_16x16x32_bf16 v[16:19], v[106:109], v[102:105], v[16:19]
	v_mfma_f32_16x16x32_bf16 v[12:15], v[106:109], v[110:113], v[12:15]
	v_mfma_f32_16x16x32_bf16 v[8:11], v[106:109], v[118:121], v[8:11]
	v_mfma_f32_16x16x32_bf16 v[4:7], v[114:117], v[94:97], v[4:7]
	v_mfma_f32_16x16x32_bf16 v[0:3], v[114:117], v[102:105], v[0:3]
	v_mfma_f32_16x16x32_bf16 v[60:63], v[114:117], v[110:113], v[60:63]
	v_mfma_f32_16x16x32_bf16 v[56:59], v[114:117], v[118:121], v[56:59]
	s_waitcnt vmcnt(0) lgkmcnt(0)
	s_barrier
	v_add_u32_e32 v128, s10, v85
	s_add_i32 s10, s12, 32
	v_add_u32_e32 v134, s10, v88
	v_add_u32_e32 v135, s10, v89
	v_add_u32_e32 v132, v134, v87
	v_add_u32_e32 v133, v135, v87
	ds_read_b128 v[90:93], v132
	ds_read_b128 v[98:101], v132 offset:2048
	ds_read_b128 v[106:109], v132 offset:4096
	ds_read_b128 v[114:117], v132 offset:6144
	ds_read_b128 v[94:97], v133 offset:16384
	ds_read_b128 v[102:105], v133 offset:18432
	ds_read_b128 v[110:113], v133 offset:20480
	ds_read_b128 v[118:121], v133 offset:22528
	v_readfirstlane_b32 s12, v128
	s_mov_b32 m0, s12
	v_mfma_f32_16x16x32_bf16 v[52:55], v[152:155], v[168:171], v[52:55]
	global_load_lds_dwordx4 v64, s[98:99]
	v_mfma_f32_16x16x32_bf16 v[48:51], v[152:155], v[172:175], v[48:51]
	s_add_i32 m0, s12, 0x4000
	v_mfma_f32_16x16x32_bf16 v[44:47], v[152:155], v[176:179], v[44:47]
	global_load_lds_dwordx4 v72, s[100:101]
	v_mfma_f32_16x16x32_bf16 v[40:43], v[152:155], v[180:183], v[40:43]
	s_add_i32 m0, s12, 0x400
	v_mfma_f32_16x16x32_bf16 v[36:39], v[156:159], v[168:171], v[36:39]
	global_load_lds_dwordx4 v66, s[98:99]
	v_mfma_f32_16x16x32_bf16 v[32:35], v[156:159], v[172:175], v[32:35]
	s_add_i32 m0, s12, 0x4400
	v_mfma_f32_16x16x32_bf16 v[28:31], v[156:159], v[176:179], v[28:31]
	global_load_lds_dwordx4 v74, s[100:101]
	v_mfma_f32_16x16x32_bf16 v[24:27], v[156:159], v[180:183], v[24:27]
	s_add_i32 m0, s12, 0x800
	v_mfma_f32_16x16x32_bf16 v[20:23], v[160:163], v[168:171], v[20:23]
	global_load_lds_dwordx4 v68, s[98:99]
	v_mfma_f32_16x16x32_bf16 v[16:19], v[160:163], v[172:175], v[16:19]
	s_add_i32 m0, s12, 0x4800
	v_mfma_f32_16x16x32_bf16 v[12:15], v[160:163], v[176:179], v[12:15]
	global_load_lds_dwordx4 v76, s[100:101]
	v_mfma_f32_16x16x32_bf16 v[8:11], v[160:163], v[180:183], v[8:11]
	s_add_i32 m0, s12, 0xc00
	v_mfma_f32_16x16x32_bf16 v[4:7], v[164:167], v[168:171], v[4:7]
	global_load_lds_dwordx4 v70, s[98:99]
	v_mfma_f32_16x16x32_bf16 v[0:3], v[164:167], v[172:175], v[0:3]
	s_add_i32 m0, s12, 0x4c00
	v_mfma_f32_16x16x32_bf16 v[60:63], v[164:167], v[176:179], v[60:63]
	global_load_lds_dwordx4 v78, s[100:101]
	v_mfma_f32_16x16x32_bf16 v[56:59], v[164:167], v[180:183], v[56:59]
	s_add_i32 s8, s8, 0x8000
	s_add_u32 s0, s0, 0x80
	s_addc_u32 s1, s1, 0
	s_add_u32 s98, s98, 0x80
	s_addc_u32 s99, s99, 0
	s_add_u32 s100, s100, 0x80
	s_addc_u32 s101, s101, 0
	s_cmpk_lg_i32 s0, 0x780
	s_cbranch_scc1 .Lg255_loop
	s_and_b32 s10, s8, 0x8000
	s_xor_b32 s12, s10, 0x8000
	v_add_u32_e32 v132, v134, v86
	v_add_u32_e32 v133, v135, v86
	ds_read_b128 v[152:155], v132
	ds_read_b128 v[156:159], v132 offset:2048
	ds_read_b128 v[160:163], v132 offset:4096
	ds_read_b128 v[164:167], v132 offset:6144
	s_waitcnt lgkmcnt(4)
	v_mfma_f32_16x16x32_bf16 v[52:55], v[90:93], v[94:97], v[52:55]
	v_mfma_f32_16x16x32_bf16 v[48:51], v[90:93], v[102:105], v[48:51]
	v_mfma_f32_16x16x32_bf16 v[44:47], v[90:93], v[110:113], v[44:47]
	v_mfma_f32_16x16x32_bf16 v[40:43], v[90:93], v[118:121], v[40:43]
	ds_read_b128 v[168:171], v133 offset:16384
	ds_read_b128 v[172:175], v133 offset:18432
	ds_read_b128 v[176:179], v133 offset:20480
	ds_read_b128 v[180:183], v133 offset:22528
	v_mfma_f32_16x16x32_bf16 v[36:39], v[98:101], v[94:97], v[36:39]
	v_mfma_f32_16x16x32_bf16 v[32:35], v[98:101], v[102:105], v[32:35]
	v_mfma_f32_16x16x32_bf16 v[28:31], v[98:101], v[110:113], v[28:31]
	v_mfma_f32_16x16x32_bf16 v[24:27], v[98:101], v[118:121], v[24:27]
	v_mfma_f32_16x16x32_bf16 v[20:23], v[106:109], v[94:97], v[20:23]
	v_mfma_f32_16x16x32_bf16 v[16:19], v[106:109], v[102:105], v[16:19]
	v_mfma_f32_16x16x32_bf16 v[12:15], v[106:109], v[110:113], v[12:15]
	v_mfma_f32_16x16x32_bf16 v[8:11], v[106:109], v[118:121], v[8:11]
	v_mfma_f32_16x16x32_bf16 v[4:7], v[114:117], v[94:97], v[4:7]
	v_mfma_f32_16x16x32_bf16 v[0:3], v[114:117], v[102:105], v[0:3]
	v_mfma_f32_16x16x32_bf16 v[60:63], v[114:117], v[110:113], v[60:63]
	v_mfma_f32_16x16x32_bf16 v[56:59], v[114:117], v[118:121], v[56:59]
	s_waitcnt vmcnt(0) lgkmcnt(0)
	s_barrier
	v_mfma_f32_16x16x32_bf16 v[52:55], v[152:155], v[168:171], v[52:55]
	v_mfma_f32_16x16x32_bf16 v[48:51], v[152:155], v[172:175], v[48:51]
	v_mfma_f32_16x16x32_bf16 v[44:47], v[152:155], v[176:179], v[44:47]
	v_mfma_f32_16x16x32_bf16 v[40:43], v[152:155], v[180:183], v[40:43]
	v_mfma_f32_16x16x32_bf16 v[36:39], v[156:159], v[168:171], v[36:39]
	v_mfma_f32_16x16x32_bf16 v[32:35], v[156:159], v[172:175], v[32:35]
	v_mfma_f32_16x16x32_bf16 v[28:31], v[156:159], v[176:179], v[28:31]
	v_mfma_f32_16x16x32_bf16 v[24:27], v[156:159], v[180:183], v[24:27]
	v_mfma_f32_16x16x32_bf16 v[20:23], v[160:163], v[168:171], v[20:23]
	v_mfma_f32_16x16x32_bf16 v[16:19], v[160:163], v[172:175], v[16:19]
	v_mfma_f32_16x16x32_bf16 v[12:15], v[160:163], v[176:179], v[12:15]
	v_mfma_f32_16x16x32_bf16 v[8:11], v[160:163], v[180:183], v[8:11]
	v_mfma_f32_16x16x32_bf16 v[4:7], v[164:167], v[168:171], v[4:7]
	v_mfma_f32_16x16x32_bf16 v[0:3], v[164:167], v[172:175], v[0:3]
	v_mfma_f32_16x16x32_bf16 v[60:63], v[164:167], v[176:179], v[60:63]
	v_mfma_f32_16x16x32_bf16 v[56:59], v[164:167], v[180:183], v[56:59]
	v_add_u32_e32 v112, 32, v88
	v_add_u32_e32 v100, v112, v87
	ds_read_b128 v[92:95], v100 offset:36864
	ds_read_b128 v[64:67], v100 offset:32768
	ds_read_b128 v[72:75], v100 offset:38912
	ds_read_b128 v[100:103], v100 offset:34816
	v_add_u32_e32 v85, 32, v89
	v_add_u32_e32 v87, v85, v87
	ds_read_b128 v[88:91], v87 offset:53248
	ds_read_b128 v[68:71], v87 offset:55296
	ds_read_b128 v[76:79], v87 offset:49152
	ds_read_b128 v[96:99], v87 offset:51200
	s_waitcnt lgkmcnt(3)
	v_mfma_f32_16x16x32_bf16 v[108:111], v[92:95], v[88:91], v[12:15]
	v_and_or_b32 v81, v81, 64, s3
	s_movk_i32 s0, 0x3fff
	s_nop 0
	v_add_u32_e32 v12, v112, v86
	s_waitcnt lgkmcnt(1)
	v_mfma_f32_16x16x32_bf16 v[52:55], v[64:67], v[76:79], v[52:55]
	v_add_u32_e32 v13, v85, v86
	s_waitcnt lgkmcnt(0)
	v_mfma_f32_16x16x32_bf16 v[48:51], v[64:67], v[96:99], v[48:51]
	v_mfma_f32_16x16x32_bf16 v[104:107], v[64:67], v[88:91], v[44:47]
	v_mfma_f32_16x16x32_bf16 v[40:43], v[64:67], v[68:71], v[40:43]
	v_mfma_f32_16x16x32_bf16 v[36:39], v[100:103], v[76:79], v[36:39]
	v_mfma_f32_16x16x32_bf16 v[32:35], v[100:103], v[96:99], v[32:35]
	v_mfma_f32_16x16x32_bf16 v[64:67], v[100:103], v[88:91], v[28:31]
	v_mfma_f32_16x16x32_bf16 v[24:27], v[100:103], v[68:71], v[24:27]
	v_mfma_f32_16x16x32_bf16 v[100:103], v[92:95], v[76:79], v[20:23]
	v_mfma_f32_16x16x32_bf16 v[16:19], v[92:95], v[96:99], v[16:19]
	v_mfma_f32_16x16x32_bf16 v[8:11], v[92:95], v[68:71], v[8:11]
	v_mfma_f32_16x16x32_bf16 v[76:79], v[72:75], v[76:79], v[4:7]
	v_mfma_f32_16x16x32_bf16 v[0:3], v[72:75], v[96:99], v[0:3]
	v_mfma_f32_16x16x32_bf16 v[88:91], v[72:75], v[88:91], v[60:63]
	v_mfma_f32_16x16x32_bf16 v[68:71], v[72:75], v[68:71], v[56:59]
	ds_read_b128 v[4:7], v12 offset:32768
	ds_read_b128 v[96:99], v12 offset:36864
	ds_read_b128 v[116:119], v12 offset:38912
	ds_read_b128 v[56:59], v12 offset:34816
	ds_read_b128 v[72:75], v13 offset:49152
	ds_read_b128 v[92:95], v13 offset:51200
	ds_read_b128 v[112:115], v13 offset:53248
	ds_read_b128 v[120:123], v13 offset:55296
	s_waitcnt lgkmcnt(3)
	v_mfma_f32_16x16x32_bf16 v[60:63], v[4:7], v[72:75], v[52:55]
	s_waitcnt vmcnt(0)
	s_waitcnt lgkmcnt(0)
	s_barrier
	v_mfma_f32_16x16x32_bf16 v[44:47], v[4:7], v[92:95], v[48:51]
	v_mfma_f32_16x16x32_bf16 v[28:31], v[4:7], v[112:115], v[104:107]
	v_mfma_f32_16x16x32_bf16 v[12:15], v[4:7], v[120:123], v[40:43]
	v_mfma_f32_16x16x32_bf16 v[52:55], v[56:59], v[72:75], v[36:39]
	v_mfma_f32_16x16x32_bf16 v[36:39], v[56:59], v[92:95], v[32:35]
	v_mfma_f32_16x16x32_bf16 v[20:23], v[56:59], v[112:115], v[64:67]
	v_mfma_f32_16x16x32_bf16 v[4:7], v[56:59], v[120:123], v[24:27]
	s_nop 1
	v_or_b32_e32 v66, v81, v84
	v_cmp_lt_i32_e32 vcc, s0, v66
	v_mfma_f32_16x16x32_bf16 v[56:59], v[96:99], v[72:75], v[100:103]
	v_mfma_f32_16x16x32_bf16 v[40:43], v[96:99], v[92:95], v[16:19]
	v_mfma_f32_16x16x32_bf16 v[24:27], v[96:99], v[112:115], v[108:111]
	v_mfma_f32_16x16x32_bf16 v[8:11], v[96:99], v[120:123], v[8:11]
	v_mfma_f32_16x16x32_bf16 v[48:51], v[116:119], v[72:75], v[76:79]
	v_mfma_f32_16x16x32_bf16 v[32:35], v[116:119], v[92:95], v[0:3]
	v_mfma_f32_16x16x32_bf16 v[16:19], v[116:119], v[112:115], v[88:91]
	v_mfma_f32_16x16x32_bf16 v[0:3], v[116:119], v[120:123], v[68:71]
	s_and_saveexec_b64 s[0:1], vcc
	s_xor_b64 s[0:1], exec, s[0:1]
	s_addk_i32 s3, 0xc000
	s_lshr_b32 s3, s3, 8
	v_and_b32_e32 v64, 0xcf, v66
	v_or_b32_e32 v192, 0x2000, v64
	v_mov_b32_e32 v65, s3
	s_andn2_saveexec_b64 s[0:1], s[0:1]
	s_ashr_i32 s3, s13, 13
	v_and_b32_e32 v192, 0x1fcf, v66
	v_mov_b32_e32 v65, s3
	s_or_b64 exec, exec, s[0:1]
	v_add_u32_e32 v64, s2, v83
	s_movk_i32 s0, 0x17f
	v_cmp_lt_i32_e64 s[48:49], s0, v64
	s_movk_i32 s0, 0x480
	s_movk_i32 s2, 0x780
	v_subrev_co_u32_e32 v67, vcc, 0x380, v64
	v_cmp_gt_u32_e64 s[42:43], s0, v64
	s_movk_i32 s0, 0x47f
	v_cmp_eq_u32_e64 s[2:3], s2, v64
	s_xor_b64 s[88:89], vcc, -1
	v_cmp_lt_u32_e32 vcc, s0, v64
	v_and_b32_e32 v68, 0x7fffff80, v64
	s_movk_i32 s0, 0x700
	v_writelane_b32 v255, s2, 20
	v_cmp_ne_u32_e64 s[0:1], s0, v68
	s_and_b64 s[14:15], vcc, s[0:1]
	v_writelane_b32 v255, s3, 21
	s_movk_i32 s2, 0x680
	v_subrev_co_u32_e32 v68, vcc, 0x700, v64
	v_cmp_gt_u32_e64 s[44:45], s2, v64
	s_movk_i32 s2, 0x280
	v_mov_b32_e32 v69, 0xfffff980
	v_mov_b32_e32 v70, 0xfffffb80
	v_ashrrev_i32_e32 v78, 6, v68
	v_lshrrev_b32_e32 v79, 6, v67
	v_mov_b32_e32 v67, 0xfffffd80
	v_mov_b32_e32 v68, 0xfffffe80
	v_cmp_gt_u32_e64 s[40:41], s2, v64
	v_cndmask_b32_e64 v69, v69, v70, s[44:45]
	v_add_u32_e32 v69, v69, v64
	v_cndmask_b32_e64 v67, v67, v68, s[40:41]
	v_add_u32_e32 v67, v67, v64
	s_xor_b64 s[0:1], vcc, -1
	v_lshlrev_b32_e32 v76, 3, v80
	v_lshlrev_b32_e32 v74, 2, v80
	v_lshrrev_b32_e32 v75, 6, v69
	v_ashrrev_i32_e32 v77, 5, v67
	v_cmp_gt_u32_e64 s[38:39], 16, v82
	s_and_saveexec_b64 s[2:3], s[48:49]
	s_xor_b64 s[90:91], exec, s[2:3]
	s_cbranch_execz .LBB0_286
	v_cmp_gt_u32_e64 s[50:51], s33, v192
	s_and_saveexec_b64 s[2:3], s[88:89]
	s_xor_b64 s[92:93], exec, s[2:3]
	s_cbranch_execz .LBB0_279
	s_and_saveexec_b64 s[2:3], s[14:15]
	s_xor_b64 s[94:95], exec, s[2:3]
	s_cbranch_execz .LBB0_276
	s_and_saveexec_b64 s[2:3], s[0:1]
	s_xor_b64 s[46:47], exec, s[2:3]
	s_cbranch_execz .LBB0_269
	s_mov_b64 vcc, exec
	v_readlane_b32 s2, v255, 20
	v_readlane_b32 s3, v255, 21
	s_and_b64 s[2:3], vcc, s[2:3]
	s_mov_b64 exec, s[2:3]
	s_cbranch_execz .LBB0_268
	s_and_saveexec_b64 s[2:3], s[50:51]
	s_cbranch_execz .LBB0_267
	v_readlane_b32 s16, v254, 9
	v_lshlrev_b32_e32 v48, 7, v192
	v_mov_b32_e32 v49, v193
	v_readlane_b32 s24, v254, 17
	v_readlane_b32 s25, v254, 18
	v_lshlrev_b32_e32 v50, 2, v76
	v_mov_b32_e32 v51, v193
	v_lshl_add_u64 v[48:49], s[24:25], 0, v[48:49]
	v_lshl_add_u64 v[56:57], v[48:49], 0, v[50:51]
	global_load_dwordx4 v[48:51], v[56:57], off
	s_nop 0
	global_load_dwordx4 v[56:59], v[56:57], off offset:16
	v_readlane_b32 s30, v254, 23
	v_readlane_b32 s31, v254, 24
	s_movk_i32 s30, 0x4000
	s_mov_b32 s31, s9
	v_readlane_b32 s17, v254, 10
	v_readlane_b32 s18, v254, 11
	v_readlane_b32 s19, v254, 12
	v_readlane_b32 s20, v254, 13
	v_readlane_b32 s21, v254, 14
	v_readlane_b32 s22, v254, 15
	v_readlane_b32 s23, v254, 16
	v_readlane_b32 s26, v254, 19
	v_readlane_b32 s27, v254, 20
	v_readlane_b32 s28, v254, 21
	v_readlane_b32 s29, v254, 22
	s_waitcnt vmcnt(1)
	v_mov_b32_e32 v68, v49
	s_waitcnt vmcnt(0)
	v_mov_b32_e32 v70, v57
	v_mov_b32_e32 v71, v59
	v_mov_b32_e32 v69, v51
	v_mov_b32_e32 v57, v58
	v_mov_b32_e32 v49, v50
	v_pk_mul_f32 v[50:51], v[54:55], v[70:71]
	v_pk_mul_f32 v[58:59], v[52:53], v[68:69]
	v_pk_mul_f32 v[52:53], v[52:53], v[48:49]
	v_pk_mul_f32 v[54:55], v[54:55], v[56:57]
	v_pk_fma_f32 v[50:51], v[62:63], v[56:57], v[50:51] neg_lo:[0,0,1] neg_hi:[0,0,1]
	v_pk_fma_f32 v[48:49], v[60:61], v[48:49], v[58:59] neg_lo:[0,0,1] neg_hi:[0,0,1]
	v_pk_fma_f32 v[54:55], v[62:63], v[70:71], v[54:55]
	v_pk_fma_f32 v[52:53], v[60:61], v[68:69], v[52:53]
	v_mov_b64_e32 v[62:63], v[50:51]
	v_mov_b64_e32 v[60:61], v[48:49]
